# sequence-DFT phase: stage-A Wb fragment loads (4 per iteration) and all 16 stage-C Wc fragment loads issued ahead into distinct registers with counted vmcnt
# speedup vs baseline: 1.0171x; 1.0004x over previous
.LBB0_1229:
	v_lshl_add_u64 v[152:153], v[150:151], 0, s[0:1]
	v_add_co_u32_e32 v152, vcc, s57, v152
	v_add_u32_e32 v186, 0x400, v169
	s_nop 0
	v_addc_co_u32_e32 v153, vcc, 0, v153, vcc
	global_load_dwordx4 v[170:173], v[152:153], off
	global_load_dwordx4 v[188:191], v[152:153], off offset:32
	global_load_dwordx4 v[192:195], v[152:153], off offset:64
	global_load_dwordx4 v[196:199], v[152:153], off offset:96
	ds_read2_b32 v[182:183], v169 offset1:32
	ds_read2_b32 v[174:175], v169 offset0:128 offset1:160
	ds_read2_b32 v[184:185], v186 offset1:32
	ds_read2_b32 v[176:177], v186 offset0:128 offset1:160
	v_add_u32_e32 v187, 0x1400, v169
	s_add_u32 s0, s0, 0x80
	s_waitcnt lgkmcnt(3)
	v_mov_b32_e32 v178, v182
	s_waitcnt lgkmcnt(2)
	v_mov_b32_e32 v179, v174
	s_waitcnt lgkmcnt(0)
	v_mov_b32_e32 v181, v176
	v_mov_b32_e32 v174, v183
	v_mov_b32_e32 v176, v185
	v_mov_b32_e32 v180, v184
	s_addc_u32 s1, s1, 0
	s_cmpk_lg_i32 s0, 0x200
	s_waitcnt vmcnt(3)
	v_mfma_f32_32x32x16_bf16 v[32:47], v[170:173], v[174:177], v[32:47]
	ds_read2_b32 v[182:183], v169 offset0:64 offset1:96
	ds_read2_b32 v[174:175], v169 offset0:192 offset1:224
	ds_read2_b32 v[184:185], v186 offset0:64 offset1:96
	ds_read2_b32 v[176:177], v186 offset0:192 offset1:224
	v_add_u32_e32 v186, 0x1000, v169
	v_mfma_f32_32x32x16_bf16 v[48:63], v[170:173], v[178:181], v[48:63]
	s_waitcnt lgkmcnt(3)
	v_mov_b32_e32 v178, v182
	s_waitcnt lgkmcnt(2)
	v_mov_b32_e32 v179, v174
	s_waitcnt lgkmcnt(1)
	v_mov_b32_e32 v180, v184
	s_waitcnt lgkmcnt(0)
	v_mov_b32_e32 v181, v176
	v_mov_b32_e32 v174, v183
	v_mov_b32_e32 v176, v185
	v_mfma_f32_32x32x16_bf16 v[16:31], v[170:173], v[178:181], v[16:31]
	s_nop 0
	v_mfma_f32_32x32x16_bf16 v[0:15], v[170:173], v[174:177], v[0:15]
	ds_read2_b32 v[182:183], v186 offset1:32
	ds_read2_b32 v[174:175], v186 offset0:128 offset1:160
	ds_read2_b32 v[184:185], v187 offset1:32
	ds_read2_b32 v[176:177], v187 offset0:128 offset1:160
	s_waitcnt lgkmcnt(3)
	v_mov_b32_e32 v178, v182
	s_waitcnt lgkmcnt(2)
	v_mov_b32_e32 v179, v174
	s_waitcnt lgkmcnt(0)
	v_mov_b32_e32 v181, v176
	v_mov_b32_e32 v174, v183
	v_mov_b32_e32 v176, v185
	v_mov_b32_e32 v180, v184
	s_waitcnt vmcnt(2)
	v_mfma_f32_32x32x16_bf16 v[32:47], v[188:191], v[174:177], v[32:47]
	ds_read2_b32 v[182:183], v186 offset0:64 offset1:96
	ds_read2_b32 v[174:175], v186 offset0:192 offset1:224
	ds_read2_b32 v[184:185], v187 offset0:64 offset1:96
	ds_read2_b32 v[176:177], v187 offset0:192 offset1:224
	v_add_u32_e32 v186, 0x2000, v169
	v_add_u32_e32 v187, 0x2400, v169
	v_mfma_f32_32x32x16_bf16 v[48:63], v[188:191], v[178:181], v[48:63]
	s_waitcnt lgkmcnt(3)
	v_mov_b32_e32 v178, v182
	s_waitcnt lgkmcnt(2)
	v_mov_b32_e32 v179, v174
	s_waitcnt lgkmcnt(1)
	v_mov_b32_e32 v180, v184
	s_waitcnt lgkmcnt(0)
	v_mov_b32_e32 v181, v176
	v_mov_b32_e32 v174, v183
	v_mov_b32_e32 v176, v185
	v_mfma_f32_32x32x16_bf16 v[16:31], v[188:191], v[178:181], v[16:31]
	s_nop 0
	v_mfma_f32_32x32x16_bf16 v[0:15], v[188:191], v[174:177], v[0:15]
	ds_read2_b32 v[182:183], v186 offset1:32
	ds_read2_b32 v[174:175], v186 offset0:128 offset1:160
	ds_read2_b32 v[184:185], v187 offset1:32
	ds_read2_b32 v[176:177], v187 offset0:128 offset1:160
	s_waitcnt lgkmcnt(3)
	v_mov_b32_e32 v178, v182
	s_waitcnt lgkmcnt(2)
	v_mov_b32_e32 v179, v174
	s_waitcnt lgkmcnt(0)
	v_mov_b32_e32 v181, v176
	v_mov_b32_e32 v174, v183
	v_mov_b32_e32 v176, v185
	v_mov_b32_e32 v180, v184
	s_waitcnt vmcnt(1)
	v_mfma_f32_32x32x16_bf16 v[32:47], v[192:195], v[174:177], v[32:47]
	ds_read2_b32 v[182:183], v186 offset0:64 offset1:96
	ds_read2_b32 v[174:175], v186 offset0:192 offset1:224
	ds_read2_b32 v[184:185], v187 offset0:64 offset1:96
	ds_read2_b32 v[176:177], v187 offset0:192 offset1:224
	v_mfma_f32_32x32x16_bf16 v[48:63], v[192:195], v[178:181], v[48:63]
	s_waitcnt lgkmcnt(3)
	v_mov_b32_e32 v178, v182
	s_waitcnt lgkmcnt(2)
	v_mov_b32_e32 v179, v174
	s_waitcnt lgkmcnt(1)
	v_mov_b32_e32 v180, v184
	s_waitcnt lgkmcnt(0)
	v_mov_b32_e32 v181, v176
	v_mov_b32_e32 v174, v183
	v_mov_b32_e32 v176, v185
	v_add_u32_e32 v184, 0x3000, v169
	v_mfma_f32_32x32x16_bf16 v[16:31], v[192:195], v[178:181], v[16:31]
	v_add_u32_e32 v185, 0x3400, v169
	v_add_u32_e32 v169, 0x4000, v169
	v_mfma_f32_32x32x16_bf16 v[0:15], v[192:195], v[174:177], v[0:15]
	ds_read2_b32 v[152:153], v184 offset1:32
	ds_read2_b32 v[174:175], v184 offset0:128 offset1:160
	ds_read2_b32 v[182:183], v185 offset1:32
	ds_read2_b32 v[176:177], v185 offset0:128 offset1:160
	s_waitcnt lgkmcnt(3)
	v_mov_b32_e32 v178, v152
	s_waitcnt lgkmcnt(2)
	v_mov_b32_e32 v179, v174
	s_waitcnt lgkmcnt(0)
	v_mov_b32_e32 v181, v176
	v_mov_b32_e32 v174, v153
	v_mov_b32_e32 v176, v183
	v_mov_b32_e32 v180, v182
	s_waitcnt vmcnt(0)
	v_mfma_f32_32x32x16_bf16 v[32:47], v[196:199], v[174:177], v[32:47]
	ds_read2_b32 v[152:153], v184 offset0:64 offset1:96
	ds_read2_b32 v[174:175], v184 offset0:192 offset1:224
	ds_read2_b32 v[182:183], v185 offset0:64 offset1:96
	ds_read2_b32 v[176:177], v185 offset0:192 offset1:224
	v_mfma_f32_32x32x16_bf16 v[48:63], v[196:199], v[178:181], v[48:63]
	s_waitcnt lgkmcnt(3)
	v_mov_b32_e32 v178, v152
	s_waitcnt lgkmcnt(2)
	v_mov_b32_e32 v179, v174
	s_waitcnt lgkmcnt(1)
	v_mov_b32_e32 v180, v182
	s_waitcnt lgkmcnt(0)
	v_mov_b32_e32 v181, v176
	v_mov_b32_e32 v174, v153
	v_mov_b32_e32 v176, v183
	v_mfma_f32_32x32x16_bf16 v[16:31], v[196:199], v[178:181], v[16:31]
	s_nop 0
	v_mfma_f32_32x32x16_bf16 v[0:15], v[196:199], v[174:177], v[0:15]
	s_cbranch_scc1 .LBB0_1229
	global_load_dwordx2 v[188:189], v[66:67], off
	global_load_dwordx2 v[190:191], v[68:69], off
	global_load_dwordx2 v[192:193], v[70:71], off
	global_load_dwordx2 v[194:195], v[72:73], off
	global_load_dwordx2 v[196:197], v[74:75], off
	global_load_dwordx2 v[198:199], v[76:77], off
	global_load_dwordx2 v[200:201], v[78:79], off
	global_load_dwordx2 v[202:203], v[80:81], off
	global_load_dwordx2 v[204:205], v[82:83], off
	global_load_dwordx2 v[206:207], v[84:85], off
	global_load_dwordx2 v[224:225], v[86:87], off
	global_load_dwordx2 v[226:227], v[88:89], off
	global_load_dwordx2 v[228:229], v[90:91], off
	global_load_dwordx2 v[230:231], v[92:93], off
	global_load_dwordx2 v[232:233], v[94:95], off
	global_load_dwordx2 v[234:235], v[96:97], off
	s_mov_b64 s[0:1], s[8:9]
	s_lshl_b32 s4, s6, 5
	s_lshl_b32 s5, s6, 2
	s_and_b32 s4, s4, 0xffffe000
	s_and_b32 s5, s5, 0x3fc
	s_waitcnt vmcnt(15)
	v_mul_f32_e32 v169, v49, v189
	v_fmac_f32_e32 v169, v48, v188
	v_mul_f32_e32 v48, v48, v189
	v_fma_f32 v48, v49, v188, -v48
	v_bfe_u32 v49, v169, 16, 1
	v_add3_u32 v49, v169, v49, s94
	v_bfe_u32 v152, v48, 16, 1
	v_lshrrev_b32_e32 v49, 16, v49
	v_add3_u32 v48, v48, v152, s94
	v_and_or_b32 v48, v48, s86, v49
	v_add_u32_e32 v49, v156, v158
	ds_write_b32 v49, v48
	global_load_dwordx2 v[188:189], v[98:99], off
	s_waitcnt vmcnt(15)
	v_mul_f32_e32 v152, v51, v191
	v_fmac_f32_e32 v152, v50, v190
	v_mul_f32_e32 v49, v50, v191
	v_fma_f32 v48, v51, v190, -v49
	v_bfe_u32 v49, v152, 16, 1
	v_add3_u32 v49, v152, v49, s94
	v_bfe_u32 v50, v48, 16, 1
	v_lshrrev_b32_e32 v49, 16, v49
	v_add3_u32 v48, v48, v50, s94
	v_and_or_b32 v48, v48, s86, v49
	v_add_u32_e32 v49, v156, v159
	ds_write_b32 v49, v48
	global_load_dwordx2 v[190:191], v[100:101], off
	s_waitcnt vmcnt(15)
	v_mul_f32_e32 v50, v53, v193
	v_fmac_f32_e32 v50, v52, v192
	v_mul_f32_e32 v49, v52, v193
	v_fma_f32 v48, v53, v192, -v49
	v_bfe_u32 v49, v50, 16, 1
	v_add3_u32 v49, v50, v49, s94
	v_bfe_u32 v50, v48, 16, 1
	v_lshrrev_b32_e32 v49, 16, v49
	v_add3_u32 v48, v48, v50, s94
	v_and_or_b32 v48, v48, s86, v49
	v_add_u32_e32 v49, v156, v160
	ds_write_b32 v49, v48
	global_load_dwordx2 v[192:193], v[102:103], off
	s_waitcnt vmcnt(15)
	v_mul_f32_e32 v50, v55, v195
	v_fmac_f32_e32 v50, v54, v194
	v_mul_f32_e32 v49, v54, v195
	v_fma_f32 v48, v55, v194, -v49
	v_bfe_u32 v49, v50, 16, 1
	v_add3_u32 v49, v50, v49, s94
	v_bfe_u32 v50, v48, 16, 1
	v_lshrrev_b32_e32 v49, 16, v49
	v_add3_u32 v48, v48, v50, s94
	v_and_or_b32 v48, v48, s86, v49
	v_add_u32_e32 v49, v156, v161
	ds_write_b32 v49, v48
	global_load_dwordx2 v[194:195], v[104:105], off
	s_waitcnt vmcnt(15)
	v_mul_f32_e32 v50, v57, v197
	v_fmac_f32_e32 v50, v56, v196
	v_mul_f32_e32 v49, v56, v197
	v_fma_f32 v48, v57, v196, -v49
	v_bfe_u32 v49, v50, 16, 1
	v_add3_u32 v49, v50, v49, s94
	v_bfe_u32 v50, v48, 16, 1
	v_lshrrev_b32_e32 v49, 16, v49
	v_add3_u32 v48, v48, v50, s94
	v_and_or_b32 v48, v48, s86, v49
	v_add_u32_e32 v49, v156, v162
	ds_write_b32 v49, v48
	global_load_dwordx2 v[196:197], v[106:107], off
	s_waitcnt vmcnt(15)
	v_mul_f32_e32 v50, v59, v199
	v_fmac_f32_e32 v50, v58, v198
	v_mul_f32_e32 v49, v58, v199
	v_fma_f32 v48, v59, v198, -v49
	v_bfe_u32 v49, v50, 16, 1
	v_add3_u32 v49, v50, v49, s94
	v_bfe_u32 v50, v48, 16, 1
	v_lshrrev_b32_e32 v49, 16, v49
	v_add3_u32 v48, v48, v50, s94
	v_and_or_b32 v48, v48, s86, v49
	v_add_u32_e32 v49, v156, v163
	ds_write_b32 v49, v48
	global_load_dwordx2 v[198:199], v[108:109], off
	s_waitcnt vmcnt(15)
	v_mul_f32_e32 v50, v61, v201
	v_fmac_f32_e32 v50, v60, v200
	v_mul_f32_e32 v49, v60, v201
	v_fma_f32 v48, v61, v200, -v49
	v_bfe_u32 v49, v50, 16, 1
	v_add3_u32 v49, v50, v49, s94
	v_bfe_u32 v50, v48, 16, 1
	v_lshrrev_b32_e32 v49, 16, v49
	v_add3_u32 v48, v48, v50, s94
	v_and_or_b32 v48, v48, s86, v49
	v_add_u32_e32 v49, v156, v164
	ds_write_b32 v49, v48
	global_load_dwordx2 v[200:201], v[110:111], off
	s_waitcnt vmcnt(15)
	v_mul_f32_e32 v50, v63, v203
	v_fmac_f32_e32 v50, v62, v202
	v_mul_f32_e32 v49, v62, v203
	v_fma_f32 v48, v63, v202, -v49
	v_bfe_u32 v49, v50, 16, 1
	v_add3_u32 v49, v50, v49, s94
	v_bfe_u32 v50, v48, 16, 1
	v_lshrrev_b32_e32 v49, 16, v49
	v_add3_u32 v48, v48, v50, s94
	v_and_or_b32 v48, v48, s86, v49
	v_add_u32_e32 v49, v156, v165
	ds_write_b32 v49, v48
	global_load_dwordx2 v[202:203], v[112:113], off
	s_waitcnt vmcnt(15)
	v_mul_f32_e32 v50, v33, v205
	v_fmac_f32_e32 v50, v32, v204
	v_mul_f32_e32 v32, v32, v205
	v_fma_f32 v32, v33, v204, -v32
	v_bfe_u32 v33, v50, 16, 1
	v_add3_u32 v33, v50, v33, s94
	v_bfe_u32 v48, v32, 16, 1
	v_lshrrev_b32_e32 v33, 16, v33
	v_add3_u32 v32, v32, v48, s94
	v_and_or_b32 v32, v32, s86, v33
	v_add_u32_e32 v33, v166, v158
	ds_write_b32 v33, v32
	global_load_dwordx2 v[204:205], v[114:115], off
	s_waitcnt vmcnt(15)
	v_mul_f32_e32 v48, v35, v207
	v_fmac_f32_e32 v48, v34, v206
	v_mul_f32_e32 v33, v34, v207
	v_fma_f32 v32, v35, v206, -v33
	v_bfe_u32 v33, v48, 16, 1
	v_add3_u32 v33, v48, v33, s94
	v_bfe_u32 v34, v32, 16, 1
	v_lshrrev_b32_e32 v33, 16, v33
	v_add3_u32 v32, v32, v34, s94
	v_and_or_b32 v32, v32, s86, v33
	v_add_u32_e32 v33, v166, v159
	ds_write_b32 v33, v32
	global_load_dwordx2 v[206:207], v[116:117], off
	s_waitcnt vmcnt(15)
	v_mul_f32_e32 v34, v37, v225
	v_fmac_f32_e32 v34, v36, v224
	v_mul_f32_e32 v33, v36, v225
	v_fma_f32 v32, v37, v224, -v33
	v_bfe_u32 v33, v34, 16, 1
	v_add3_u32 v33, v34, v33, s94
	v_bfe_u32 v34, v32, 16, 1
	v_lshrrev_b32_e32 v33, 16, v33
	v_add3_u32 v32, v32, v34, s94
	v_and_or_b32 v32, v32, s86, v33
	v_add_u32_e32 v33, v166, v160
	ds_write_b32 v33, v32
	global_load_dwordx2 v[224:225], v[118:119], off
	s_waitcnt vmcnt(15)
	v_mul_f32_e32 v34, v39, v227
	v_fmac_f32_e32 v34, v38, v226
	v_mul_f32_e32 v33, v38, v227
	v_fma_f32 v32, v39, v226, -v33
	v_bfe_u32 v33, v34, 16, 1
	v_add3_u32 v33, v34, v33, s94
	v_bfe_u32 v34, v32, 16, 1
	v_lshrrev_b32_e32 v33, 16, v33
	v_add3_u32 v32, v32, v34, s94
	v_and_or_b32 v32, v32, s86, v33
	v_add_u32_e32 v33, v166, v161
	ds_write_b32 v33, v32
	global_load_dwordx2 v[226:227], v[120:121], off
	s_waitcnt vmcnt(15)
	v_mul_f32_e32 v34, v41, v229
	v_fmac_f32_e32 v34, v40, v228
	v_mul_f32_e32 v33, v40, v229
	v_fma_f32 v32, v41, v228, -v33
	v_bfe_u32 v33, v34, 16, 1
	v_add3_u32 v33, v34, v33, s94
	v_bfe_u32 v34, v32, 16, 1
	v_lshrrev_b32_e32 v33, 16, v33
	v_add3_u32 v32, v32, v34, s94
	v_and_or_b32 v32, v32, s86, v33
	v_add_u32_e32 v33, v166, v162
	ds_write_b32 v33, v32
	global_load_dwordx2 v[228:229], v[122:123], off
	s_waitcnt vmcnt(15)
	v_mul_f32_e32 v34, v43, v231
	v_fmac_f32_e32 v34, v42, v230
	v_mul_f32_e32 v33, v42, v231
	v_fma_f32 v32, v43, v230, -v33
	v_bfe_u32 v33, v34, 16, 1
	v_add3_u32 v33, v34, v33, s94
	v_bfe_u32 v34, v32, 16, 1
	v_lshrrev_b32_e32 v33, 16, v33
	v_add3_u32 v32, v32, v34, s94
	v_and_or_b32 v32, v32, s86, v33
	v_add_u32_e32 v33, v166, v163
	ds_write_b32 v33, v32
	global_load_dwordx2 v[230:231], v[124:125], off
	s_waitcnt vmcnt(15)
	v_mul_f32_e32 v34, v45, v233
	v_fmac_f32_e32 v34, v44, v232
	v_mul_f32_e32 v33, v44, v233
	v_fma_f32 v32, v45, v232, -v33
	v_bfe_u32 v33, v34, 16, 1
	v_add3_u32 v33, v34, v33, s94
	v_bfe_u32 v34, v32, 16, 1
	v_lshrrev_b32_e32 v33, 16, v33
	v_add3_u32 v32, v32, v34, s94
	v_and_or_b32 v32, v32, s86, v33
	v_add_u32_e32 v33, v166, v164
	ds_write_b32 v33, v32
	global_load_dwordx2 v[232:233], v[126:127], off
	s_waitcnt vmcnt(15)
	v_mul_f32_e32 v34, v47, v235
	v_fmac_f32_e32 v34, v46, v234
	v_mul_f32_e32 v33, v46, v235
	v_fma_f32 v32, v47, v234, -v33
	v_bfe_u32 v33, v34, 16, 1
	v_add3_u32 v33, v34, v33, s94
	v_bfe_u32 v34, v32, 16, 1
	v_lshrrev_b32_e32 v33, 16, v33
	v_add3_u32 v32, v32, v34, s94
	v_and_or_b32 v32, v32, s86, v33
	v_add_u32_e32 v33, v166, v165
	ds_write_b32 v33, v32
	global_load_dwordx2 v[234:235], v[128:129], off
	s_waitcnt vmcnt(15)
	v_mul_f32_e32 v34, v17, v189
	v_fmac_f32_e32 v34, v16, v188
	v_mul_f32_e32 v16, v16, v189
	v_fma_f32 v16, v17, v188, -v16
	v_bfe_u32 v17, v34, 16, 1
	v_add3_u32 v17, v34, v17, s94
	v_bfe_u32 v32, v16, 16, 1
	v_lshrrev_b32_e32 v17, 16, v17
	v_add3_u32 v16, v16, v32, s94
	v_and_or_b32 v16, v16, s86, v17
	v_add_u32_e32 v17, v167, v158
	ds_write_b32 v17, v16
	s_waitcnt vmcnt(14)
	v_mul_f32_e32 v32, v19, v191
	v_fmac_f32_e32 v32, v18, v190
	v_mul_f32_e32 v17, v18, v191
	v_fma_f32 v16, v19, v190, -v17
	v_bfe_u32 v17, v32, 16, 1
	v_add3_u32 v17, v32, v17, s94
	v_bfe_u32 v18, v16, 16, 1
	v_lshrrev_b32_e32 v17, 16, v17
	v_add3_u32 v16, v16, v18, s94
	v_and_or_b32 v16, v16, s86, v17
	v_add_u32_e32 v17, v167, v159
	ds_write_b32 v17, v16
	s_waitcnt vmcnt(13)
	v_mul_f32_e32 v18, v21, v193
	v_fmac_f32_e32 v18, v20, v192
	v_mul_f32_e32 v17, v20, v193
	v_fma_f32 v16, v21, v192, -v17
	v_bfe_u32 v17, v18, 16, 1
	v_add3_u32 v17, v18, v17, s94
	v_bfe_u32 v18, v16, 16, 1
	v_lshrrev_b32_e32 v17, 16, v17
	v_add3_u32 v16, v16, v18, s94
	v_and_or_b32 v16, v16, s86, v17
	v_add_u32_e32 v17, v167, v160
	ds_write_b32 v17, v16
	s_waitcnt vmcnt(12)
	v_mul_f32_e32 v18, v23, v195
	v_fmac_f32_e32 v18, v22, v194
	v_mul_f32_e32 v17, v22, v195
	v_fma_f32 v16, v23, v194, -v17
	v_bfe_u32 v17, v18, 16, 1
	v_add3_u32 v17, v18, v17, s94
	v_bfe_u32 v18, v16, 16, 1
	v_lshrrev_b32_e32 v17, 16, v17
	v_add3_u32 v16, v16, v18, s94
	v_and_or_b32 v16, v16, s86, v17
	v_add_u32_e32 v17, v167, v161
	ds_write_b32 v17, v16
	s_waitcnt vmcnt(11)
	v_mul_f32_e32 v18, v25, v197
	v_fmac_f32_e32 v18, v24, v196
	v_mul_f32_e32 v17, v24, v197
	v_fma_f32 v16, v25, v196, -v17
	v_bfe_u32 v17, v18, 16, 1
	v_add3_u32 v17, v18, v17, s94
	v_bfe_u32 v18, v16, 16, 1
	v_lshrrev_b32_e32 v17, 16, v17
	v_add3_u32 v16, v16, v18, s94
	v_and_or_b32 v16, v16, s86, v17
	v_add_u32_e32 v17, v167, v162
	ds_write_b32 v17, v16
	s_waitcnt vmcnt(10)
	v_mul_f32_e32 v18, v27, v199
	v_fmac_f32_e32 v18, v26, v198
	v_mul_f32_e32 v17, v26, v199
	v_fma_f32 v16, v27, v198, -v17
	v_bfe_u32 v17, v18, 16, 1
	v_add3_u32 v17, v18, v17, s94
	v_bfe_u32 v18, v16, 16, 1
	v_lshrrev_b32_e32 v17, 16, v17
	v_add3_u32 v16, v16, v18, s94
	v_and_or_b32 v16, v16, s86, v17
	v_add_u32_e32 v17, v167, v163
	ds_write_b32 v17, v16
	s_waitcnt vmcnt(9)
	v_mul_f32_e32 v18, v29, v201
	v_fmac_f32_e32 v18, v28, v200
	v_mul_f32_e32 v17, v28, v201
	v_fma_f32 v16, v29, v200, -v17
	v_bfe_u32 v17, v18, 16, 1
	v_add3_u32 v17, v18, v17, s94
	v_bfe_u32 v18, v16, 16, 1
	v_lshrrev_b32_e32 v17, 16, v17
	v_add3_u32 v16, v16, v18, s94
	v_and_or_b32 v16, v16, s86, v17
	v_add_u32_e32 v17, v167, v164
	ds_write_b32 v17, v16
	s_waitcnt vmcnt(8)
	v_mul_f32_e32 v18, v31, v203
	v_fmac_f32_e32 v18, v30, v202
	v_mul_f32_e32 v17, v30, v203
	v_fma_f32 v16, v31, v202, -v17
	v_bfe_u32 v17, v18, 16, 1
	v_add3_u32 v17, v18, v17, s94
	v_bfe_u32 v18, v16, 16, 1
	v_lshrrev_b32_e32 v17, 16, v17
	v_add3_u32 v16, v16, v18, s94
	v_and_or_b32 v16, v16, s86, v17
	v_add_u32_e32 v17, v167, v165
	ds_write_b32 v17, v16
	s_waitcnt vmcnt(7)
	v_mul_f32_e32 v18, v1, v205
	v_fmac_f32_e32 v18, v0, v204
	v_mul_f32_e32 v0, v0, v205
	v_fma_f32 v0, v1, v204, -v0
	v_bfe_u32 v1, v18, 16, 1
	v_add3_u32 v1, v18, v1, s94
	v_bfe_u32 v16, v0, 16, 1
	v_lshrrev_b32_e32 v1, 16, v1
	v_add3_u32 v0, v0, v16, s94
	v_and_or_b32 v0, v0, s86, v1
	v_add_u32_e32 v1, v168, v158
	ds_write_b32 v1, v0
	s_waitcnt vmcnt(6)
	v_mul_f32_e32 v16, v3, v207
	v_fmac_f32_e32 v16, v2, v206
	v_mul_f32_e32 v1, v2, v207
	v_fma_f32 v0, v3, v206, -v1
	v_bfe_u32 v1, v16, 16, 1
	v_add3_u32 v1, v16, v1, s94
	v_bfe_u32 v2, v0, 16, 1
	v_lshrrev_b32_e32 v1, 16, v1
	v_add3_u32 v0, v0, v2, s94
	v_and_or_b32 v0, v0, s86, v1
	v_add_u32_e32 v1, v168, v159
	ds_write_b32 v1, v0
	s_waitcnt vmcnt(5)
	v_mul_f32_e32 v2, v5, v225
	v_fmac_f32_e32 v2, v4, v224
	v_mul_f32_e32 v1, v4, v225
	v_fma_f32 v0, v5, v224, -v1
	v_bfe_u32 v1, v2, 16, 1
	v_add3_u32 v1, v2, v1, s94
	v_bfe_u32 v2, v0, 16, 1
	v_lshrrev_b32_e32 v1, 16, v1
	v_add3_u32 v0, v0, v2, s94
	v_and_or_b32 v0, v0, s86, v1
	v_add_u32_e32 v1, v168, v160
	ds_write_b32 v1, v0
	s_waitcnt vmcnt(4)
	v_mul_f32_e32 v2, v7, v227
	v_fmac_f32_e32 v2, v6, v226
	v_mul_f32_e32 v1, v6, v227
	v_fma_f32 v0, v7, v226, -v1
	v_bfe_u32 v1, v2, 16, 1
	v_add3_u32 v1, v2, v1, s94
	v_bfe_u32 v2, v0, 16, 1
	v_lshrrev_b32_e32 v1, 16, v1
	v_add3_u32 v0, v0, v2, s94
	v_and_or_b32 v0, v0, s86, v1
	v_add_u32_e32 v1, v168, v161
	ds_write_b32 v1, v0
	s_waitcnt vmcnt(3)
	v_mul_f32_e32 v2, v9, v229
	v_fmac_f32_e32 v2, v8, v228
	v_mul_f32_e32 v1, v8, v229
	v_fma_f32 v0, v9, v228, -v1
	v_bfe_u32 v1, v2, 16, 1
	v_add3_u32 v1, v2, v1, s94
	v_bfe_u32 v2, v0, 16, 1
	v_lshrrev_b32_e32 v1, 16, v1
	v_add3_u32 v0, v0, v2, s94
	v_and_or_b32 v0, v0, s86, v1
	v_add_u32_e32 v1, v168, v162
	ds_write_b32 v1, v0
	s_waitcnt vmcnt(2)
	v_mul_f32_e32 v2, v11, v231
	v_fmac_f32_e32 v2, v10, v230
	v_mul_f32_e32 v1, v10, v231
	v_fma_f32 v0, v11, v230, -v1
	v_bfe_u32 v1, v2, 16, 1
	v_add3_u32 v1, v2, v1, s94
	v_bfe_u32 v2, v0, 16, 1
	v_lshrrev_b32_e32 v1, 16, v1
	v_add3_u32 v0, v0, v2, s94
	v_and_or_b32 v0, v0, s86, v1
	v_add_u32_e32 v1, v168, v163
	ds_write_b32 v1, v0
	s_waitcnt vmcnt(1)
	v_mul_f32_e32 v2, v13, v233
	v_fmac_f32_e32 v2, v12, v232
	v_mul_f32_e32 v1, v12, v233
	v_fma_f32 v0, v13, v232, -v1
	v_bfe_u32 v1, v2, 16, 1
	v_add3_u32 v1, v2, v1, s94
	v_bfe_u32 v2, v0, 16, 1
	v_lshrrev_b32_e32 v1, 16, v1
	v_add3_u32 v0, v0, v2, s94
	v_and_or_b32 v0, v0, s86, v1
	v_add_u32_e32 v1, v168, v164
	ds_write_b32 v1, v0
	s_waitcnt vmcnt(0)
	v_mul_f32_e32 v2, v15, v235
	v_fmac_f32_e32 v2, v14, v234
	v_mul_f32_e32 v1, v14, v235
	v_fma_f32 v0, v15, v234, -v1
	v_bfe_u32 v1, v2, 16, 1
	v_add3_u32 v1, v2, v1, s94
	v_bfe_u32 v2, v0, 16, 1
	v_lshrrev_b32_e32 v1, 16, v1
	v_add3_u32 v0, v0, v2, s94
	v_and_or_b32 v0, v0, s86, v1
	v_add_u32_e32 v1, v168, v165
	ds_write_b32 v1, v0
	s_waitcnt lgkmcnt(0)
	s_barrier
	global_load_dwordx4 v[40:43], v[130:131], off
	global_load_dwordx4 v[44:47], v[132:133], off
	global_load_dwordx4 v[48:51], v[130:131], off offset:32
	global_load_dwordx4 v[52:55], v[134:135], off
	global_load_dwordx4 v[56:59], v[130:131], off offset:64
	global_load_dwordx4 v[60:63], v[136:137], off
	global_load_dwordx4 v[172:175], v[130:131], off offset:96
	global_load_dwordx4 v[176:179], v[138:139], off
	global_load_dwordx4 v[180:183], v[130:131], off offset:128
	global_load_dwordx4 v[184:187], v[140:141], off
	global_load_dwordx4 v[188:191], v[130:131], off offset:160
	global_load_dwordx4 v[192:195], v[142:143], off
	global_load_dwordx4 v[196:199], v[130:131], off offset:192
	global_load_dwordx4 v[200:203], v[144:145], off
	global_load_dwordx4 v[204:207], v[130:131], off offset:224
	global_load_dwordx4 v[224:227], v[146:147], off
	ds_read_b128 v[4:7], v65
	ds_read_b128 v[32:35], v65 offset:32
	s_waitcnt vmcnt(15) lgkmcnt(1)
	v_mfma_f32_32x32x16_bf16 v[16:31], v[40:43], v[4:7], 0
	s_waitcnt vmcnt(13) lgkmcnt(0)
	v_mfma_f32_32x32x16_bf16 v[16:31], v[48:51], v[32:35], v[16:31]
	v_mfma_f32_32x32x16_bf16 v[0:15], v[44:47], v[4:7], 0
	s_waitcnt vmcnt(12)
	v_mfma_f32_32x32x16_bf16 v[0:15], v[52:55], v[32:35], v[0:15]
	ds_read_b128 v[32:35], v65 offset:64
	s_waitcnt vmcnt(11) lgkmcnt(0)
	v_mfma_f32_32x32x16_bf16 v[16:31], v[56:59], v[32:35], v[16:31]
	s_waitcnt vmcnt(10)
	v_mfma_f32_32x32x16_bf16 v[0:15], v[60:63], v[32:35], v[0:15]
	ds_read_b128 v[32:35], v65 offset:96
	s_waitcnt vmcnt(9) lgkmcnt(0)
	v_mfma_f32_32x32x16_bf16 v[16:31], v[172:175], v[32:35], v[16:31]
	s_waitcnt vmcnt(8)
	v_mfma_f32_32x32x16_bf16 v[0:15], v[176:179], v[32:35], v[0:15]
	ds_read_b128 v[32:35], v65 offset:128
	s_waitcnt vmcnt(7) lgkmcnt(0)
	v_mfma_f32_32x32x16_bf16 v[16:31], v[180:183], v[32:35], v[16:31]
	s_waitcnt vmcnt(6)
	v_mfma_f32_32x32x16_bf16 v[0:15], v[184:187], v[32:35], v[0:15]
	ds_read_b128 v[32:35], v65 offset:160
	s_waitcnt vmcnt(5) lgkmcnt(0)
	v_mfma_f32_32x32x16_bf16 v[16:31], v[188:191], v[32:35], v[16:31]
	s_waitcnt vmcnt(4)
	v_mfma_f32_32x32x16_bf16 v[0:15], v[192:195], v[32:35], v[0:15]
	ds_read_b128 v[32:35], v65 offset:192
	s_waitcnt vmcnt(3) lgkmcnt(0)
	v_mfma_f32_32x32x16_bf16 v[16:31], v[196:199], v[32:35], v[16:31]
	s_waitcnt vmcnt(2)
	v_mfma_f32_32x32x16_bf16 v[0:15], v[200:203], v[32:35], v[0:15]
	ds_read_b128 v[32:35], v65 offset:224
	s_waitcnt vmcnt(1) lgkmcnt(0)
	v_mfma_f32_32x32x16_bf16 v[16:31], v[204:207], v[32:35], v[16:31]
	s_nop 11
	v_mul_f32_e32 v16, 0x3a800000, v16
	s_waitcnt vmcnt(0)
	v_mfma_f32_32x32x16_bf16 v[0:15], v[224:227], v[32:35], v[0:15]
	v_mov_b32_e32 v34, v154
	s_add_u32 s0, s0, s5
	v_and_or_b32 v32, v34, 30, s12
	v_ashrrev_i32_e32 v35, 1, v32
	v_and_b32_e32 v32, 1, v34
	v_lshlrev_b32_e32 v34, 4, v34
	v_and_b32_e32 v34, 0xfffffe00, v34
	s_addc_u32 s1, s1, 0
	v_lshlrev_b32_e32 v208, 1, v32
	v_add3_u32 v34, v35, s4, v34
	v_lshl_add_u64 v[32:33], s[0:1], 0, v[208:209]
	s_mov_b64 s[0:1], 0xf900000
	v_bfe_u32 v36, v16, 16, 1
	v_ashrrev_i32_e32 v35, 31, v34
	v_lshl_add_u64 v[32:33], v[32:33], 0, s[0:1]
	v_add3_u32 v16, v16, v36, s94
	v_lshlrev_b64 v[36:37], 10, v[34:35]
	v_lshl_add_u64 v[36:37], v[32:33], 0, v[36:37]
	flat_store_short_d16_hi v[36:37], v16
	v_mul_f32_e32 v16, 0x3a800000, v17
	v_bfe_u32 v17, v16, 16, 1
	v_add3_u32 v35, v16, v17, s94
	v_add_u32_e32 v16, 0x80, v34
	v_ashrrev_i32_e32 v17, 31, v16
	v_lshlrev_b64 v[16:17], 10, v[16:17]
	v_lshl_add_u64 v[16:17], v[32:33], 0, v[16:17]
	flat_store_short_d16_hi v[16:17], v35
	v_mul_f32_e32 v16, 0x3a800000, v18
	v_bfe_u32 v17, v16, 16, 1
	v_add3_u32 v18, v16, v17, s94
	v_add_u32_e32 v16, 0x100, v34
	v_ashrrev_i32_e32 v17, 31, v16
	v_lshlrev_b64 v[16:17], 10, v[16:17]
	v_lshl_add_u64 v[16:17], v[32:33], 0, v[16:17]
	flat_store_short_d16_hi v[16:17], v18
	v_mul_f32_e32 v16, 0x3a800000, v19
	v_bfe_u32 v17, v16, 16, 1
	v_add3_u32 v18, v16, v17, s94
	v_add_u32_e32 v16, 0x180, v34
	v_ashrrev_i32_e32 v17, 31, v16
	v_lshlrev_b64 v[16:17], 10, v[16:17]
	v_lshl_add_u64 v[16:17], v[32:33], 0, v[16:17]
	flat_store_short_d16_hi v[16:17], v18
	v_mul_f32_e32 v16, 0x3a800000, v20
	v_bfe_u32 v17, v16, 16, 1
	v_add3_u32 v18, v16, v17, s94
	v_add_u32_e32 v16, 0x400, v34
	v_ashrrev_i32_e32 v17, 31, v16
	v_lshlrev_b64 v[16:17], 10, v[16:17]
	v_lshl_add_u64 v[16:17], v[32:33], 0, v[16:17]
	flat_store_short_d16_hi v[16:17], v18
	v_mul_f32_e32 v16, 0x3a800000, v21
	v_bfe_u32 v17, v16, 16, 1
	v_add3_u32 v18, v16, v17, s94
	v_add_u32_e32 v16, 0x480, v34
	v_ashrrev_i32_e32 v17, 31, v16
	v_lshlrev_b64 v[16:17], 10, v[16:17]
	v_lshl_add_u64 v[16:17], v[32:33], 0, v[16:17]
	flat_store_short_d16_hi v[16:17], v18
	v_mul_f32_e32 v16, 0x3a800000, v22
	v_bfe_u32 v17, v16, 16, 1
	v_add3_u32 v18, v16, v17, s94
	v_add_u32_e32 v16, 0x500, v34
	v_ashrrev_i32_e32 v17, 31, v16
	v_lshlrev_b64 v[16:17], 10, v[16:17]
	v_lshl_add_u64 v[16:17], v[32:33], 0, v[16:17]
	flat_store_short_d16_hi v[16:17], v18
	v_mul_f32_e32 v16, 0x3a800000, v23
	v_bfe_u32 v17, v16, 16, 1
	v_add3_u32 v18, v16, v17, s94
	v_add_u32_e32 v16, 0x580, v34
	v_ashrrev_i32_e32 v17, 31, v16
	v_lshlrev_b64 v[16:17], 10, v[16:17]
	v_lshl_add_u64 v[16:17], v[32:33], 0, v[16:17]
	flat_store_short_d16_hi v[16:17], v18
	v_mul_f32_e32 v16, 0x3a800000, v24
	v_bfe_u32 v17, v16, 16, 1
	v_add3_u32 v18, v16, v17, s94
	v_add_u32_e32 v16, 0x800, v34
	v_ashrrev_i32_e32 v17, 31, v16
	v_lshlrev_b64 v[16:17], 10, v[16:17]
	v_lshl_add_u64 v[16:17], v[32:33], 0, v[16:17]
	flat_store_short_d16_hi v[16:17], v18
	v_mul_f32_e32 v16, 0x3a800000, v25
	v_bfe_u32 v17, v16, 16, 1
	v_add3_u32 v18, v16, v17, s94
	v_add_u32_e32 v16, 0x880, v34
	v_ashrrev_i32_e32 v17, 31, v16
	v_lshlrev_b64 v[16:17], 10, v[16:17]
	v_lshl_add_u64 v[16:17], v[32:33], 0, v[16:17]
	flat_store_short_d16_hi v[16:17], v18
	v_mul_f32_e32 v16, 0x3a800000, v26
	v_bfe_u32 v17, v16, 16, 1
	v_add3_u32 v18, v16, v17, s94
	v_add_u32_e32 v16, 0x900, v34
	v_ashrrev_i32_e32 v17, 31, v16
	v_lshlrev_b64 v[16:17], 10, v[16:17]
	v_lshl_add_u64 v[16:17], v[32:33], 0, v[16:17]
	flat_store_short_d16_hi v[16:17], v18
	v_mul_f32_e32 v16, 0x3a800000, v27
	v_bfe_u32 v17, v16, 16, 1
	v_add3_u32 v18, v16, v17, s94
	v_add_u32_e32 v16, 0x980, v34
	v_ashrrev_i32_e32 v17, 31, v16
	v_lshlrev_b64 v[16:17], 10, v[16:17]
	v_lshl_add_u64 v[16:17], v[32:33], 0, v[16:17]
	flat_store_short_d16_hi v[16:17], v18
	v_mul_f32_e32 v16, 0x3a800000, v28
	v_bfe_u32 v17, v16, 16, 1
	v_add3_u32 v18, v16, v17, s94
	v_add_u32_e32 v16, 0xc00, v34
	v_ashrrev_i32_e32 v17, 31, v16
	v_lshlrev_b64 v[16:17], 10, v[16:17]
	v_lshl_add_u64 v[16:17], v[32:33], 0, v[16:17]
	flat_store_short_d16_hi v[16:17], v18
	v_mul_f32_e32 v16, 0x3a800000, v29
	v_bfe_u32 v17, v16, 16, 1
	v_add3_u32 v18, v16, v17, s94
	v_add_u32_e32 v16, 0xc80, v34
	v_ashrrev_i32_e32 v17, 31, v16
	v_lshlrev_b64 v[16:17], 10, v[16:17]
	v_lshl_add_u64 v[16:17], v[32:33], 0, v[16:17]
	flat_store_short_d16_hi v[16:17], v18
	v_mul_f32_e32 v16, 0x3a800000, v30
	v_bfe_u32 v17, v16, 16, 1
	v_add3_u32 v18, v16, v17, s94
	v_add_u32_e32 v16, 0xd00, v34
	v_ashrrev_i32_e32 v17, 31, v16
	v_lshlrev_b64 v[16:17], 10, v[16:17]
	v_lshl_add_u64 v[16:17], v[32:33], 0, v[16:17]
	flat_store_short_d16_hi v[16:17], v18
	v_mul_f32_e32 v16, 0x3a800000, v31
	v_bfe_u32 v17, v16, 16, 1
	v_add3_u32 v18, v16, v17, s94
	v_add_u32_e32 v16, 0xd80, v34
	v_ashrrev_i32_e32 v17, 31, v16
	v_lshlrev_b64 v[16:17], 10, v[16:17]
	v_lshl_add_u64 v[16:17], v[32:33], 0, v[16:17]
	v_mul_f32_e32 v0, 0x3a800000, v0
	flat_store_short_d16_hi v[16:17], v18
	v_bfe_u32 v16, v0, 16, 1
	v_add3_u32 v0, v0, v16, s94
	v_add_u32_e32 v16, 0x1000, v34
	v_ashrrev_i32_e32 v17, 31, v16
	v_lshlrev_b64 v[16:17], 10, v[16:17]
	v_lshl_add_u64 v[16:17], v[32:33], 0, v[16:17]
	flat_store_short_d16_hi v[16:17], v0
	v_mul_f32_e32 v0, 0x3a800000, v1
	v_bfe_u32 v1, v0, 16, 1
	v_add3_u32 v16, v0, v1, s94
	v_add_u32_e32 v0, 0x1080, v34
	v_ashrrev_i32_e32 v1, 31, v0
	v_lshlrev_b64 v[0:1], 10, v[0:1]
	v_lshl_add_u64 v[0:1], v[32:33], 0, v[0:1]
	flat_store_short_d16_hi v[0:1], v16
	v_mul_f32_e32 v0, 0x3a800000, v2
	v_bfe_u32 v1, v0, 16, 1
	v_add3_u32 v2, v0, v1, s94
	v_add_u32_e32 v0, 0x1100, v34
	v_ashrrev_i32_e32 v1, 31, v0
	v_lshlrev_b64 v[0:1], 10, v[0:1]
	v_lshl_add_u64 v[0:1], v[32:33], 0, v[0:1]
	flat_store_short_d16_hi v[0:1], v2
	v_mul_f32_e32 v0, 0x3a800000, v3
	v_bfe_u32 v1, v0, 16, 1
	v_add3_u32 v2, v0, v1, s94
	v_add_u32_e32 v0, 0x1180, v34
	v_ashrrev_i32_e32 v1, 31, v0
	v_lshlrev_b64 v[0:1], 10, v[0:1]
	v_lshl_add_u64 v[0:1], v[32:33], 0, v[0:1]
	flat_store_short_d16_hi v[0:1], v2
	v_mul_f32_e32 v0, 0x3a800000, v4
	v_bfe_u32 v1, v0, 16, 1
	v_add3_u32 v2, v0, v1, s94
	v_add_u32_e32 v0, 0x1400, v34
	v_ashrrev_i32_e32 v1, 31, v0
	v_lshlrev_b64 v[0:1], 10, v[0:1]
	v_lshl_add_u64 v[0:1], v[32:33], 0, v[0:1]
	flat_store_short_d16_hi v[0:1], v2
	v_mul_f32_e32 v0, 0x3a800000, v5
	v_bfe_u32 v1, v0, 16, 1
	v_add3_u32 v2, v0, v1, s94
	v_add_u32_e32 v0, 0x1480, v34
	v_ashrrev_i32_e32 v1, 31, v0
	v_lshlrev_b64 v[0:1], 10, v[0:1]
	v_lshl_add_u64 v[0:1], v[32:33], 0, v[0:1]
	flat_store_short_d16_hi v[0:1], v2
	v_mul_f32_e32 v0, 0x3a800000, v6
	v_bfe_u32 v1, v0, 16, 1
	v_add3_u32 v2, v0, v1, s94
	v_add_u32_e32 v0, 0x1500, v34
	v_ashrrev_i32_e32 v1, 31, v0
	v_lshlrev_b64 v[0:1], 10, v[0:1]
	v_lshl_add_u64 v[0:1], v[32:33], 0, v[0:1]
	flat_store_short_d16_hi v[0:1], v2
	v_mul_f32_e32 v0, 0x3a800000, v7
	v_bfe_u32 v1, v0, 16, 1
	v_add3_u32 v2, v0, v1, s94
	v_add_u32_e32 v0, 0x1580, v34
	v_ashrrev_i32_e32 v1, 31, v0
	v_lshlrev_b64 v[0:1], 10, v[0:1]
	v_lshl_add_u64 v[0:1], v[32:33], 0, v[0:1]
	flat_store_short_d16_hi v[0:1], v2
	v_mul_f32_e32 v0, 0x3a800000, v8
	v_bfe_u32 v1, v0, 16, 1
	v_add3_u32 v2, v0, v1, s94
	v_add_u32_e32 v0, 0x1800, v34
	v_ashrrev_i32_e32 v1, 31, v0
	v_lshlrev_b64 v[0:1], 10, v[0:1]
	v_lshl_add_u64 v[0:1], v[32:33], 0, v[0:1]
	flat_store_short_d16_hi v[0:1], v2
	v_mul_f32_e32 v0, 0x3a800000, v9
	v_bfe_u32 v1, v0, 16, 1
	v_add3_u32 v2, v0, v1, s94
	v_add_u32_e32 v0, 0x1880, v34
	v_ashrrev_i32_e32 v1, 31, v0
	v_lshlrev_b64 v[0:1], 10, v[0:1]
	v_lshl_add_u64 v[0:1], v[32:33], 0, v[0:1]
	flat_store_short_d16_hi v[0:1], v2
	v_mul_f32_e32 v0, 0x3a800000, v10
	v_bfe_u32 v1, v0, 16, 1
	v_add3_u32 v2, v0, v1, s94
	v_add_u32_e32 v0, 0x1900, v34
	v_ashrrev_i32_e32 v1, 31, v0
	v_lshlrev_b64 v[0:1], 10, v[0:1]
	v_lshl_add_u64 v[0:1], v[32:33], 0, v[0:1]
	flat_store_short_d16_hi v[0:1], v2
	v_mul_f32_e32 v0, 0x3a800000, v11
	v_bfe_u32 v1, v0, 16, 1
	v_add3_u32 v2, v0, v1, s94
	v_add_u32_e32 v0, 0x1980, v34
	v_ashrrev_i32_e32 v1, 31, v0
	v_lshlrev_b64 v[0:1], 10, v[0:1]
	v_lshl_add_u64 v[0:1], v[32:33], 0, v[0:1]
	flat_store_short_d16_hi v[0:1], v2
	v_mul_f32_e32 v0, 0x3a800000, v12
	v_bfe_u32 v1, v0, 16, 1
	v_add3_u32 v2, v0, v1, s94
	v_add_u32_e32 v0, 0x1c00, v34
	v_ashrrev_i32_e32 v1, 31, v0
	v_lshlrev_b64 v[0:1], 10, v[0:1]
	v_lshl_add_u64 v[0:1], v[32:33], 0, v[0:1]
	flat_store_short_d16_hi v[0:1], v2
	v_mul_f32_e32 v0, 0x3a800000, v13
	v_bfe_u32 v1, v0, 16, 1
	v_add3_u32 v2, v0, v1, s94
	v_add_u32_e32 v0, 0x1c80, v34
	v_ashrrev_i32_e32 v1, 31, v0
	v_lshlrev_b64 v[0:1], 10, v[0:1]
	v_lshl_add_u64 v[0:1], v[32:33], 0, v[0:1]
	flat_store_short_d16_hi v[0:1], v2
	v_mul_f32_e32 v0, 0x3a800000, v14
	v_bfe_u32 v1, v0, 16, 1
	v_add3_u32 v2, v0, v1, s94
	v_add_u32_e32 v0, 0x1d00, v34
	v_ashrrev_i32_e32 v1, 31, v0
	v_lshlrev_b64 v[0:1], 10, v[0:1]
	v_lshl_add_u64 v[0:1], v[32:33], 0, v[0:1]
	flat_store_short_d16_hi v[0:1], v2
	v_mul_f32_e32 v0, 0x3a800000, v15
	v_bfe_u32 v1, v0, 16, 1
	v_add3_u32 v2, v0, v1, s94
	v_add_u32_e32 v0, 0x1d80, v34
	v_ashrrev_i32_e32 v1, 31, v0
	v_lshlrev_b64 v[0:1], 10, v[0:1]
	s_add_i32 s6, s6, s52
	v_lshl_add_u64 v[0:1], v[32:33], 0, v[0:1]
	s_cmpk_lt_i32 s6, 0x200
	flat_store_short_d16_hi v[0:1], v2
	s_waitcnt lgkmcnt(0)
	s_barrier
	s_cbranch_scc1 .LBB0_1228
